# grid barrier: acquire-side buffer_inv issued early (non-leader before XGEN poll, leader right after wbl2) on top of v43
# speedup vs baseline: 1.0121x; 1.0083x over previous
.LBB0_137:
	s_lshl_b32 s0, s30, 8
	s_mov_b32 s1, 0
	v_lshl_add_u64 v[2:3], v[0:1], 0, s[0:1]
	v_add_co_u32_e32 v8, vcc, 0x1000, v2
	v_mov_b32_e32 v5, 1
	s_nop 0
	v_addc_co_u32_e32 v9, vcc, 0, v3, vcc
	global_atomic_add v5, v[8:9], v5, off offset:1024 sc0
	v_cvt_f32_u32_e32 v7, v6
	v_sub_u32_e32 v8, 0, v6
	v_rcp_iflag_f32_e32 v7, v7
	s_nop 0
	v_mul_f32_e32 v7, 0x4f7ffffe, v7
	v_cvt_u32_f32_e32 v7, v7
	v_mul_lo_u32 v8, v8, v7
	v_mul_hi_u32 v8, v7, v8
	v_add_u32_e32 v7, v7, v8
	s_waitcnt vmcnt(0)
	v_mul_hi_u32 v7, v5, v7
	v_mul_lo_u32 v9, v7, v6
	v_add_u32_e32 v8, 1, v5
	v_sub_u32_e32 v5, v5, v9
	v_add_u32_e32 v10, 1, v7
	v_cmp_ge_u32_e32 vcc, v5, v6
	v_sub_u32_e32 v9, v5, v6
	s_nop 0
	v_cndmask_b32_e32 v7, v7, v10, vcc
	v_cndmask_b32_e32 v5, v5, v9, vcc
	v_add_u32_e32 v9, 1, v7
	v_cmp_ge_u32_e32 vcc, v5, v6
	s_nop 1
	v_cndmask_b32_e32 v5, v7, v9, vcc
	v_mad_u64_u32 v[6:7], s[0:1], v6, v5, v[6:7]
	v_cmp_ne_u32_e32 vcc, v8, v6
	s_and_saveexec_b64 s[0:1], vcc
	s_xor_b64 s[0:1], exec, s[0:1]
	s_cbranch_execz .LBB0_150
	v_add_co_u32_e32 v6, vcc, 0x2000, v2
	s_nop 1
	v_addc_co_u32_e32 v7, vcc, 0, v3, vcc
	s_waitcnt lgkmcnt(0)
	buffer_inv sc1
	global_load_dword v4, v[6:7], off offset:1024 sc1
	s_waitcnt vmcnt(0)
	v_cmp_eq_u32_e32 vcc, v4, v5
	s_and_saveexec_b64 s[2:3], vcc
	s_cbranch_execz .LBB0_149
	s_mov_b64 s[4:5], 0x2400
	v_lshl_add_u64 v[2:3], v[2:3], 0, s[4:5]
	s_mov_b32 s18, 1
	s_mov_b64 s[4:5], 0
	s_branch .LBB0_141

.LBB0_149:
	s_or_b64 exec, exec, s[2:3]
	s_waitcnt vmcnt(0)
	s_waitcnt vmcnt(0)
.LBB0_150:
	s_andn2_saveexec_b64 s[0:1], s[0:1]
	s_cbranch_execz .LBB0_166
	v_add_co_u32_e32 v6, vcc, 0x3000, v0
	buffer_wbl2 sc1
	buffer_inv sc1
	s_waitcnt lgkmcnt(0)
	s_waitcnt vmcnt(0)
	v_addc_co_u32_e32 v7, vcc, 0, v1, vcc
	v_mov_b32_e32 v5, 1
	global_atomic_add v5, v[6:7], v5, off offset:1024 sc0
	v_cvt_f32_u32_e32 v6, v4
	v_sub_u32_e32 v8, 0, v4
	s_mov_b64 s[0:1], 0x3500
	s_mov_b64 s[2:3], -1
	v_rcp_iflag_f32_e32 v6, v6
	s_nop 0
	v_mul_f32_e32 v6, 0x4f7ffffe, v6
	v_cvt_u32_f32_e32 v9, v6
	v_lshl_add_u64 v[6:7], v[0:1], 0, s[0:1]
	v_mul_lo_u32 v8, v8, v9
	v_mul_hi_u32 v8, v9, v8
	v_add_u32_e32 v8, v9, v8
	s_waitcnt vmcnt(0)
	v_mul_hi_u32 v8, v5, v8
	v_mul_lo_u32 v10, v8, v4
	v_add_u32_e32 v9, 1, v5
	v_sub_u32_e32 v5, v5, v10
	v_add_u32_e32 v11, 1, v8
	v_cmp_ge_u32_e32 vcc, v5, v4
	v_sub_u32_e32 v10, v5, v4
	s_nop 0
	v_cndmask_b32_e32 v8, v8, v11, vcc
	v_cndmask_b32_e32 v5, v5, v10, vcc
	v_add_u32_e32 v10, 1, v8
	v_cmp_ge_u32_e32 vcc, v5, v4
	s_nop 1
	v_cndmask_b32_e32 v8, v8, v10, vcc
	v_mad_u64_u32 v[4:5], s[0:1], v4, v8, v[4:5]
	v_cmp_ne_u32_e32 vcc, v9, v4
	s_and_saveexec_b64 s[0:1], vcc
	s_cbranch_execz .LBB0_163
	global_load_dword v4, v[6:7], off sc1
	s_mov_b64 s[4:5], 0
	s_waitcnt vmcnt(0)
	v_cmp_eq_u32_e32 vcc, v4, v8
	s_and_saveexec_b64 s[2:3], vcc
	s_cbranch_execz .LBB0_162
	s_mov_b64 s[4:5], 0x200
	v_lshl_add_u64 v[4:5], v[0:1], 0, s[4:5]
	s_mov_b32 s16, 1
	s_mov_b64 s[4:5], 0
	s_branch .LBB0_155

.LBB0_165:
	s_or_b64 exec, exec, s[0:1]
	v_add_co_u32_e32 v0, vcc, 0x2000, v2
	v_mov_b32_e32 v2, 1
	s_nop 0
	v_addc_co_u32_e32 v1, vcc, 0, v3, vcc
	s_waitcnt vmcnt(0)
	global_atomic_add v[0:1], v2, off offset:1024
	s_waitcnt vmcnt(0)

.LBB0_195:
	s_or_b64 exec, exec, s[8:9]
	v_cvt_f32_u32_e32 v4, v2
	s_waitcnt vmcnt(0)
	v_readfirstlane_b32 s6, v3
	v_sub_u32_e32 v3, 0, v2
	v_rcp_iflag_f32_e32 v4, v4
	v_add_u32_e32 v5, s6, v1
	v_mul_f32_e32 v4, 0x4f7ffffe, v4
	v_cvt_u32_f32_e32 v4, v4
	v_mul_lo_u32 v1, v3, v4
	v_mul_hi_u32 v1, v4, v1
	v_add_u32_e32 v1, v4, v1
	v_mul_hi_u32 v1, v5, v1
	v_mul_lo_u32 v3, v1, v2
	v_sub_u32_e32 v3, v5, v3
	v_add_u32_e32 v4, 1, v1
	v_cmp_ge_u32_e32 vcc, v3, v2
	s_nop 1
	v_cndmask_b32_e32 v1, v1, v4, vcc
	v_sub_u32_e32 v4, v3, v2
	v_cndmask_b32_e32 v3, v3, v4, vcc
	v_add_u32_e32 v4, 1, v1
	v_cmp_ge_u32_e32 vcc, v3, v2
	v_add_u32_e32 v3, 1, v5
	s_nop 0
	v_cndmask_b32_e32 v1, v1, v4, vcc
	v_mul_lo_u32 v4, v2, v1
	v_add_u32_e32 v2, v4, v2
	v_cmp_ne_u32_e32 vcc, v3, v2
	s_and_saveexec_b64 s[6:7], vcc
	s_xor_b64 s[6:7], exec, s[6:7]
	s_cbranch_execz .LBB0_209
	s_waitcnt lgkmcnt(0)
	buffer_inv sc1
	global_load_dword v0, v226, s[0:1] offset:1024 sc1
	s_add_u32 s10, s0, 0x2400
	s_addc_u32 s11, s1, 0
	s_waitcnt vmcnt(0)
	v_cmp_eq_u32_e32 vcc, v0, v1
	s_and_saveexec_b64 s[8:9], vcc
	s_cbranch_execz .LBB0_208
	s_mov_b32 s22, 1
	s_mov_b64 s[12:13], 0
	s_branch .LBB0_199

.LBB0_208:
	s_or_b64 exec, exec, s[8:9]
	s_waitcnt vmcnt(0)
	s_waitcnt vmcnt(0)
.LBB0_209:
	s_andn2_saveexec_b64 s[6:7], s[6:7]
	s_cbranch_execz .LBB0_229
	s_mov_b64 s[6:7], exec
	buffer_wbl2 sc1
	buffer_inv sc1
	s_waitcnt lgkmcnt(0)
	s_waitcnt vmcnt(0)
	v_mbcnt_lo_u32_b32 v1, s6, 0
	v_mbcnt_hi_u32_b32 v1, s7, v1
	v_cmp_eq_u32_e32 vcc, 0, v1
	s_and_saveexec_b64 s[8:9], vcc
	s_cbranch_execz .LBB0_212
	s_bcnt1_i32_b64 s6, s[6:7]
	v_mov_b32_e32 v2, s6
	v_mov_b32_e32 v3, 0x3000
	global_atomic_add v2, v3, v2, s[4:5] offset:1024 sc0

.LBB0_226:
	s_or_b64 exec, exec, s[4:5]
	s_mov_b64 s[4:5], exec
	v_mbcnt_lo_u32_b32 v0, s4, 0
	v_mbcnt_hi_u32_b32 v0, s5, v0
	v_cmp_eq_u32_e32 vcc, 0, v0
	s_waitcnt vmcnt(0)
	s_and_saveexec_b64 s[6:7], vcc
	s_cbranch_execz .LBB0_228
	s_bcnt1_i32_b64 s4, s[4:5]
	v_mov_b32_e32 v0, s4
	global_atomic_add v226, v0, s[0:1] offset:1024

.LBB0_253:
	s_or_b64 exec, exec, s[8:9]
	v_cvt_f32_u32_e32 v4, v2
	s_waitcnt vmcnt(0)
	v_readfirstlane_b32 s0, v3
	v_sub_u32_e32 v3, 0, v2
	v_rcp_iflag_f32_e32 v4, v4
	v_add_u32_e32 v5, s0, v1
	v_mul_f32_e32 v4, 0x4f7ffffe, v4
	v_cvt_u32_f32_e32 v4, v4
	v_mul_lo_u32 v1, v3, v4
	v_mul_hi_u32 v1, v4, v1
	v_add_u32_e32 v1, v4, v1
	v_mul_hi_u32 v1, v5, v1
	v_mul_lo_u32 v3, v1, v2
	v_sub_u32_e32 v3, v5, v3
	v_add_u32_e32 v4, 1, v1
	v_cmp_ge_u32_e32 vcc, v3, v2
	s_nop 1
	v_cndmask_b32_e32 v1, v1, v4, vcc
	v_sub_u32_e32 v4, v3, v2
	v_cndmask_b32_e32 v3, v3, v4, vcc
	v_add_u32_e32 v4, 1, v1
	v_cmp_ge_u32_e32 vcc, v3, v2
	v_add_u32_e32 v3, 1, v5
	s_nop 0
	v_cndmask_b32_e32 v1, v1, v4, vcc
	v_mul_lo_u32 v4, v2, v1
	v_add_u32_e32 v2, v4, v2
	v_cmp_ne_u32_e32 vcc, v3, v2
	s_and_saveexec_b64 s[0:1], vcc
	s_xor_b64 s[0:1], exec, s[0:1]
	s_cbranch_execz .LBB0_267
	s_waitcnt lgkmcnt(0)
	buffer_inv sc1
	global_load_dword v0, v226, s[6:7] offset:1024 sc1
	s_add_u32 s10, s6, 0x2400
	s_addc_u32 s11, s7, 0
	s_waitcnt vmcnt(0)
	v_cmp_eq_u32_e32 vcc, v0, v1
	s_and_saveexec_b64 s[8:9], vcc
	s_cbranch_execz .LBB0_266
	s_mov_b32 s22, 1
	s_mov_b64 s[12:13], 0
	s_branch .LBB0_257

.LBB0_267:
	s_andn2_saveexec_b64 s[0:1], s[0:1]
	s_cbranch_execz .LBB0_287
	s_mov_b64 s[0:1], exec
	buffer_wbl2 sc1
	buffer_inv sc1
	s_waitcnt lgkmcnt(0)
	s_waitcnt vmcnt(0)
	v_mbcnt_lo_u32_b32 v1, s0, 0
	v_mbcnt_hi_u32_b32 v1, s1, v1
	v_cmp_eq_u32_e32 vcc, 0, v1
	s_and_saveexec_b64 s[8:9], vcc
	s_cbranch_execz .LBB0_270
	s_bcnt1_i32_b64 s0, s[0:1]
	v_mov_b32_e32 v2, s0
	v_mov_b32_e32 v3, 0x3000
	global_atomic_add v2, v3, v2, s[4:5] offset:1024 sc0

.LBB0_284:
	s_or_b64 exec, exec, s[0:1]
	s_mov_b64 s[0:1], exec
	v_mbcnt_lo_u32_b32 v0, s0, 0
	v_mbcnt_hi_u32_b32 v0, s1, v0
	v_cmp_eq_u32_e32 vcc, 0, v0
	s_waitcnt vmcnt(0)
	s_and_saveexec_b64 s[4:5], vcc
	s_cbranch_execz .LBB0_286
	s_bcnt1_i32_b64 s0, s[0:1]
	v_mov_b32_e32 v0, s0
	global_atomic_add v226, v0, s[6:7] offset:1024

.LBB0_345:
	s_andn2_saveexec_b64 s[0:1], s[0:1]
	s_cbranch_execz .LBB0_365
	s_mov_b64 s[8:9], exec
	buffer_wbl2 sc1
	buffer_inv sc1
	s_waitcnt lgkmcnt(0)
	s_waitcnt vmcnt(0)
	v_mbcnt_lo_u32_b32 v1, s8, 0
	v_mbcnt_hi_u32_b32 v1, s9, v1
	v_cmp_eq_u32_e32 vcc, 0, v1
	s_and_saveexec_b64 s[10:11], vcc
	s_cbranch_execz .LBB0_348
	s_bcnt1_i32_b64 s8, s[8:9]
	v_mov_b32_e32 v2, s8
	v_mov_b32_e32 v3, 0x3000
	global_atomic_add v2, v3, v2, s[4:5] offset:1024 sc0

.LBB0_362:
	s_or_b64 exec, exec, s[4:5]
	s_mov_b64 s[4:5], exec
	v_mbcnt_lo_u32_b32 v0, s4, 0
	v_mbcnt_hi_u32_b32 v0, s5, v0
	v_cmp_eq_u32_e32 vcc, 0, v0
	s_waitcnt vmcnt(0)
	s_and_saveexec_b64 s[8:9], vcc
	s_cbranch_execz .LBB0_364
	s_bcnt1_i32_b64 s4, s[4:5]
	v_mov_b32_e32 v0, s4
	global_atomic_add v226, v0, s[6:7] offset:1024

.LBB0_476:
	s_or_b64 exec, exec, s[8:9]
	v_cvt_f32_u32_e32 v4, v2
	s_waitcnt vmcnt(0)
	v_readfirstlane_b32 s0, v3
	v_sub_u32_e32 v3, 0, v2
	v_rcp_iflag_f32_e32 v4, v4
	v_add_u32_e32 v5, s0, v1
	v_mul_f32_e32 v4, 0x4f7ffffe, v4
	v_cvt_u32_f32_e32 v4, v4
	v_mul_lo_u32 v1, v3, v4
	v_mul_hi_u32 v1, v4, v1
	v_add_u32_e32 v1, v4, v1
	v_mul_hi_u32 v1, v5, v1
	v_mul_lo_u32 v3, v1, v2
	v_sub_u32_e32 v3, v5, v3
	v_add_u32_e32 v4, 1, v1
	v_cmp_ge_u32_e32 vcc, v3, v2
	s_nop 1
	v_cndmask_b32_e32 v1, v1, v4, vcc
	v_sub_u32_e32 v4, v3, v2
	v_cndmask_b32_e32 v3, v3, v4, vcc
	v_add_u32_e32 v4, 1, v1
	v_cmp_ge_u32_e32 vcc, v3, v2
	v_add_u32_e32 v3, 1, v5
	s_nop 0
	v_cndmask_b32_e32 v1, v1, v4, vcc
	v_mul_lo_u32 v4, v2, v1
	v_add_u32_e32 v2, v4, v2
	v_cmp_ne_u32_e32 vcc, v3, v2
	s_and_saveexec_b64 s[0:1], vcc
	s_xor_b64 s[0:1], exec, s[0:1]
	s_movk_i32 s18, 0x1fff
	s_cbranch_execz .LBB0_490
	s_waitcnt lgkmcnt(0)
	buffer_inv sc1
	global_load_dword v0, v226, s[6:7] offset:1024 sc1
	s_add_u32 s10, s6, 0x2400
	s_addc_u32 s11, s7, 0
	s_waitcnt vmcnt(0)
	v_cmp_eq_u32_e32 vcc, v0, v1
	s_and_saveexec_b64 s[8:9], vcc
	s_cbranch_execz .LBB0_489
	s_mov_b32 s22, 1
	s_mov_b64 s[12:13], 0
	s_branch .LBB0_480

.LBB0_697:
	s_or_b64 exec, exec, s[8:9]
	v_cvt_f32_u32_e32 v4, v2
	s_waitcnt vmcnt(0)
	v_readfirstlane_b32 s0, v3
	v_sub_u32_e32 v3, 0, v2
	v_rcp_iflag_f32_e32 v4, v4
	v_add_u32_e32 v5, s0, v1
	v_mul_f32_e32 v4, 0x4f7ffffe, v4
	v_cvt_u32_f32_e32 v4, v4
	v_mul_lo_u32 v1, v3, v4
	v_mul_hi_u32 v1, v4, v1
	v_add_u32_e32 v1, v4, v1
	v_mul_hi_u32 v1, v5, v1
	v_mul_lo_u32 v3, v1, v2
	v_sub_u32_e32 v3, v5, v3
	v_add_u32_e32 v4, 1, v1
	v_cmp_ge_u32_e32 vcc, v3, v2
	s_nop 1
	v_cndmask_b32_e32 v1, v1, v4, vcc
	v_sub_u32_e32 v4, v3, v2
	v_cndmask_b32_e32 v3, v3, v4, vcc
	v_add_u32_e32 v4, 1, v1
	v_cmp_ge_u32_e32 vcc, v3, v2
	v_add_u32_e32 v3, 1, v5
	s_nop 0
	v_cndmask_b32_e32 v1, v1, v4, vcc
	v_mul_lo_u32 v4, v2, v1
	v_add_u32_e32 v2, v4, v2
	v_cmp_ne_u32_e32 vcc, v3, v2
	s_and_saveexec_b64 s[0:1], vcc
	s_xor_b64 s[0:1], exec, s[0:1]
	s_movk_i32 s18, 0x1ff
	s_cbranch_execz .LBB0_711
	s_waitcnt lgkmcnt(0)
	buffer_inv sc1
	global_load_dword v0, v226, s[6:7] offset:1024 sc1
	s_add_u32 s10, s6, 0x2400
	s_addc_u32 s11, s7, 0
	s_waitcnt vmcnt(0)
	v_cmp_eq_u32_e32 vcc, v0, v1
	s_and_saveexec_b64 s[8:9], vcc
	s_cbranch_execz .LBB0_710
	s_mov_b32 s22, 1
	s_mov_b64 s[12:13], 0
	s_branch .LBB0_701

.LBB0_1011:
	s_andn2_saveexec_b64 s[6:7], s[6:7]
	s_cbranch_execz .LBB0_1031
	s_mov_b64 s[8:9], exec
	buffer_wbl2 sc1
	buffer_inv sc1
	s_waitcnt lgkmcnt(0)
	s_waitcnt vmcnt(0)
	v_mbcnt_lo_u32_b32 v1, s8, 0
	v_mbcnt_hi_u32_b32 v1, s9, v1
	v_cmp_eq_u32_e32 vcc, 0, v1
	s_and_saveexec_b64 s[10:11], vcc
	s_cbranch_execz .LBB0_1014
	s_bcnt1_i32_b64 s8, s[8:9]
	v_mov_b32_e32 v2, s8
	v_mov_b32_e32 v3, 0x3000
	global_atomic_add v2, v3, v2, s[4:5] offset:1024 sc0

.LBB0_1028:
	s_or_b64 exec, exec, s[4:5]
	s_mov_b64 s[4:5], exec
	v_mbcnt_lo_u32_b32 v0, s4, 0
	v_mbcnt_hi_u32_b32 v0, s5, v0
	v_cmp_eq_u32_e32 vcc, 0, v0
	s_waitcnt vmcnt(0)
	s_and_saveexec_b64 s[8:9], vcc
	s_cbranch_execz .LBB0_1030
	s_bcnt1_i32_b64 s4, s[4:5]
	v_mov_b32_e32 v0, s4
	global_atomic_add v226, v0, s[0:1] offset:1024

.LBB0_1434:
	s_or_b64 exec, exec, s[10:11]
	v_cvt_f32_u32_e32 v4, v2
	s_waitcnt vmcnt(0)
	v_readfirstlane_b32 s0, v3
	v_sub_u32_e32 v3, 0, v2
	v_rcp_iflag_f32_e32 v4, v4
	v_add_u32_e32 v5, s0, v1
	v_mul_f32_e32 v4, 0x4f7ffffe, v4
	v_cvt_u32_f32_e32 v4, v4
	v_mul_lo_u32 v1, v3, v4
	v_mul_hi_u32 v1, v4, v1
	v_add_u32_e32 v1, v4, v1
	v_mul_hi_u32 v1, v5, v1
	v_mul_lo_u32 v3, v1, v2
	v_sub_u32_e32 v3, v5, v3
	v_add_u32_e32 v4, 1, v1
	v_cmp_ge_u32_e32 vcc, v3, v2
	s_nop 1
	v_cndmask_b32_e32 v1, v1, v4, vcc
	v_sub_u32_e32 v4, v3, v2
	v_cndmask_b32_e32 v3, v3, v4, vcc
	v_add_u32_e32 v4, 1, v1
	v_cmp_ge_u32_e32 vcc, v3, v2
	v_add_u32_e32 v3, 1, v5
	s_nop 0
	v_cndmask_b32_e32 v1, v1, v4, vcc
	v_mul_lo_u32 v4, v2, v1
	v_add_u32_e32 v2, v4, v2
	v_cmp_ne_u32_e32 vcc, v3, v2
	s_and_saveexec_b64 s[2:3], vcc
	s_xor_b64 s[2:3], exec, s[2:3]
	s_cbranch_execz .LBB0_1448
	s_waitcnt lgkmcnt(0)
	buffer_inv sc1
	global_load_dword v0, v226, s[8:9] offset:1024 sc1
	s_add_u32 s12, s8, 0x2400
	s_addc_u32 s13, s9, 0
	s_waitcnt vmcnt(0)
	v_cmp_eq_u32_e32 vcc, v0, v1
	s_and_saveexec_b64 s[10:11], vcc
	s_cbranch_execz .LBB0_1447
	s_mov_b32 s24, 1
	s_mov_b64 s[14:15], 0
	s_branch .LBB0_1438

.LBB0_1447:
	s_or_b64 exec, exec, s[10:11]
	s_waitcnt vmcnt(0)
	s_waitcnt vmcnt(0)
.LBB0_1448:
	s_andn2_saveexec_b64 s[2:3], s[2:3]
	s_cbranch_execz .LBB0_1468
	s_mov_b64 s[2:3], exec
	buffer_wbl2 sc1
	buffer_inv sc1
	s_waitcnt lgkmcnt(0)
	s_waitcnt vmcnt(0)
	v_mbcnt_lo_u32_b32 v1, s2, 0
	v_mbcnt_hi_u32_b32 v1, s3, v1
	v_cmp_eq_u32_e32 vcc, 0, v1
	s_and_saveexec_b64 s[10:11], vcc
	s_cbranch_execz .LBB0_1451
	s_bcnt1_i32_b64 s0, s[2:3]
	v_mov_b32_e32 v2, s0
	v_mov_b32_e32 v3, 0x3000
	global_atomic_add v2, v3, v2, s[6:7] offset:1024 sc0

.LBB0_1465:
	s_or_b64 exec, exec, s[2:3]
	s_mov_b64 s[2:3], exec
	v_mbcnt_lo_u32_b32 v0, s2, 0
	v_mbcnt_hi_u32_b32 v0, s3, v0
	v_cmp_eq_u32_e32 vcc, 0, v0
	s_waitcnt vmcnt(0)
	s_and_saveexec_b64 s[6:7], vcc
	s_cbranch_execz .LBB0_1467
	s_bcnt1_i32_b64 s0, s[2:3]
	v_mov_b32_e32 v0, s0
	global_atomic_add v226, v0, s[8:9] offset:1024

.LBB0_1642:
	s_or_b64 exec, exec, s[8:9]
	v_cvt_f32_u32_e32 v4, v2
	s_waitcnt vmcnt(0)
	v_readfirstlane_b32 s0, v3
	v_sub_u32_e32 v3, 0, v2
	v_rcp_iflag_f32_e32 v4, v4
	v_add_u32_e32 v5, s0, v1
	v_mul_f32_e32 v4, 0x4f7ffffe, v4
	v_cvt_u32_f32_e32 v4, v4
	v_mul_lo_u32 v1, v3, v4
	v_mul_hi_u32 v1, v4, v1
	v_add_u32_e32 v1, v4, v1
	v_mul_hi_u32 v1, v5, v1
	v_mul_lo_u32 v3, v1, v2
	v_sub_u32_e32 v3, v5, v3
	v_add_u32_e32 v4, 1, v1
	v_cmp_ge_u32_e32 vcc, v3, v2
	s_nop 1
	v_cndmask_b32_e32 v1, v1, v4, vcc
	v_sub_u32_e32 v4, v3, v2
	v_cndmask_b32_e32 v3, v3, v4, vcc
	v_add_u32_e32 v4, 1, v1
	v_cmp_ge_u32_e32 vcc, v3, v2
	v_add_u32_e32 v3, 1, v5
	s_nop 0
	v_cndmask_b32_e32 v1, v1, v4, vcc
	v_mul_lo_u32 v4, v2, v1
	v_add_u32_e32 v2, v4, v2
	v_cmp_ne_u32_e32 vcc, v3, v2
	s_and_saveexec_b64 s[0:1], vcc
	s_xor_b64 s[0:1], exec, s[0:1]
	s_mov_b32 s18, 0x800000
	s_cbranch_execz .LBB0_1656
	s_waitcnt lgkmcnt(0)
	buffer_inv sc1
	global_load_dword v0, v226, s[6:7] offset:1024 sc1
	s_add_u32 s10, s6, 0x2400
	s_addc_u32 s11, s7, 0
	s_waitcnt vmcnt(0)
	v_cmp_eq_u32_e32 vcc, v0, v1
	s_and_saveexec_b64 s[8:9], vcc
	s_cbranch_execz .LBB0_1655
	s_mov_b32 s22, 1
	s_mov_b64 s[12:13], 0
	s_branch .LBB0_1646

.LBB0_1657:
	s_mov_b64 s[0:1], exec
	buffer_wbl2 sc1
	buffer_inv sc1
	s_waitcnt lgkmcnt(0)
	s_waitcnt vmcnt(0)
	v_mbcnt_lo_u32_b32 v1, s0, 0
	v_mbcnt_hi_u32_b32 v1, s1, v1
	v_cmp_eq_u32_e32 vcc, 0, v1
	s_and_saveexec_b64 s[8:9], vcc
	s_cbranch_execz .LBB0_1659
	s_bcnt1_i32_b64 s0, s[0:1]
	v_mov_b32_e32 v2, s0
	v_mov_b32_e32 v3, 0x3000
	global_atomic_add v2, v3, v2, s[4:5] offset:1024 sc0

.LBB0_1673:
	s_or_b64 exec, exec, s[0:1]
	s_mov_b64 s[0:1], exec
	v_mbcnt_lo_u32_b32 v0, s0, 0
	v_mbcnt_hi_u32_b32 v0, s1, v0
	v_cmp_eq_u32_e32 vcc, 0, v0
	s_waitcnt vmcnt(0)
	s_and_saveexec_b64 s[4:5], vcc
	s_cbranch_execnz .LBB0_1674
	s_getpc_b64 s[98:99]
